# phase 3 and phase 5 task indices bit-permuted so each workgroup works on its own XCD's tiles; barriers into s=3 and s=6 join the XCD-local set
# speedup vs baseline: 1.0324x; 1.0099x over previous
.LBB0_41:
	s_andn2_saveexec_b64 s[4:5], s[4:5]
	s_cbranch_execz .LBB0_61
	v_readlane_b32 s6, v255, 40
	s_cmp_eq_u32 s6, 1
	s_cbranch_scc0 .Lbar_global
	s_mul_hi_u32 s6, s17, 0x1999999a
	s_mul_i32 s6, s6, 10
	s_sub_i32 s6, s17, s6
	s_lshr_b32 s7, 0x395, s6
	s_bitcmp1_b32 s7, 0
	s_cbranch_scc1 .Lbar_local
	s_cmp_eq_u32 s6, 1
	s_cbranch_scc0 .Lbar_global
	s_cmp_gt_u32 s17, 1
	s_cbranch_scc0 .Lbar_global

.LBB0_98:
	s_and_b64 s[0:1], exec, s[54:55]
	v_ashrrev_i32_e32 v2, 2, v35
	s_movk_i32 s0, 0x1400
	v_add_u32_e32 v6, s25, v2
	v_mov_b64_e32 v[2:3], s[8:9]
	s_cselect_b32 s0, s0, 0x2480
	s_mov_b32 s1, s93
	v_mad_i64_i32 v[2:3], s[4:5], v6, s15, v[2:3]
	v_lshl_add_u64 v[2:3], v[2:3], 0, s[0:1]
	s_mov_b32 s11, s93
	v_lshl_add_u64 v[2:3], v[2:3], 0, s[10:11]
	v_lshlrev_b32_e32 v130, 2, v54
	v_lshl_add_u64 v[80:81], v[2:3], 0, v[130:131]
	s_waitcnt lgkmcnt(0)
	s_barrier
	global_load_dwordx4 v[2:5], v[80:81], off offset:48
	global_load_dwordx4 v[26:29], v[80:81], off offset:32
	s_movk_i32 s0, 0x600
	s_cselect_b32 s92, 0x400, s0
	v_readlane_b32 s68, v254, 27
	s_mov_b64 s[0:1], s[52:53]
	v_readlane_b32 s52, v254, 43
	v_readlane_b32 s82, v254, 41
	v_readlane_b32 s53, v254, 44
	v_readlane_b32 s58, v254, 49
	v_readlane_b32 s83, v254, 42
	v_readlane_b32 s59, v254, 50
	s_mov_b64 s[52:53], s[0:1]
	s_cselect_b32 s0, s82, s58
	v_readlane_b32 s4, v255, 9
	v_and_b32_e32 v7, 64, v198
	s_cselect_b32 s1, s83, s59
	v_readlane_b32 s5, v255, 10
	s_add_u32 s0, s0, s4
	v_add_u32_e32 v10, 64, v7
	v_ashrrev_i32_e32 v7, 31, v6
	s_addc_u32 s1, s1, s5
	v_readlane_b32 s4, v253, 26
	v_xor_b32_e32 v8, 1, v198
	v_lshlrev_b64 v[6:7], 11, v[6:7]
	v_readlane_b32 s5, v253, 27
	v_xor_b32_e32 v9, 2, v198
	v_cmp_lt_i32_e32 vcc, v8, v10
	v_lshl_add_u64 v[6:7], s[4:5], 0, v[6:7]
	v_lshl_add_u64 v[22:23], v[6:7], 0, s[92:93]
	v_cndmask_b32_e32 v8, v198, v8, vcc
	v_cmp_lt_i32_e32 vcc, v9, v10
	s_lshl_b32 s92, s22, 1
	v_lshl_add_u64 v[74:75], v[22:23], 0, s[92:93]
	v_cndmask_b32_e32 v9, v198, v9, vcc
	ds_read2_b32 v[30:31], v230 offset0:14 offset1:15
	ds_read2_b32 v[32:33], v230 offset0:12 offset1:13
	ds_read2_b32 v[70:71], v230 offset0:10 offset1:11
	ds_read2_b32 v[72:73], v230 offset0:8 offset1:9
	v_lshlrev_b32_e32 v69, 2, v8
	v_lshlrev_b32_e32 v231, 2, v9
	global_load_dwordx4 v[6:9], v130, s[0:1] offset:48
	global_load_dwordx4 v[10:13], v130, s[0:1] offset:32
	global_load_dwordx4 v[14:17], v130, s[0:1] offset:16
	global_load_dwordx4 v[18:21], v130, s[0:1]
	s_waitcnt lgkmcnt(2)
	v_pk_mul_f32 v[78:79], v[32:33], v[32:33]
	v_pk_mul_f32 v[76:77], v[30:31], v[30:31]
	v_readlane_b32 s69, v254, 28
	v_readlane_b32 s70, v254, 29
	v_readlane_b32 s71, v254, 30
	v_readlane_b32 s72, v254, 31
	v_readlane_b32 s73, v254, 32
	v_readlane_b32 s74, v254, 33
	v_readlane_b32 s75, v254, 34
	v_readlane_b32 s76, v254, 35
	v_readlane_b32 s77, v254, 36
	v_readlane_b32 s78, v254, 37
	v_readlane_b32 s79, v254, 38
	v_readlane_b32 s80, v254, 39
	v_readlane_b32 s81, v254, 40
	v_readlane_b32 s68, v255, 31
	v_readlane_b32 s69, v255, 32
	s_mov_b64 s[70:71], 0x100
	s_mov_b64 s[72:73], 0x180
	s_mov_b64 s[74:75], 0x200
	s_mov_b64 s[76:77], 0x280
	s_mov_b64 s[78:79], 0x300
	s_mov_b64 s[80:81], 0x380
	s_mov_b64 s[82:83], 0x780
	v_readlane_b32 s54, v254, 45
	v_readlane_b32 s55, v254, 46
	v_readlane_b32 s56, v254, 47
	v_readlane_b32 s57, v254, 48
	v_readlane_b32 s60, v254, 51
	v_readlane_b32 s61, v254, 52
	v_readlane_b32 s62, v254, 53
	v_readlane_b32 s63, v254, 54
	v_readlane_b32 s64, v254, 55
	v_readlane_b32 s65, v254, 56
	v_readlane_b32 s66, v254, 57
	v_readlane_b32 s67, v254, 58
	s_waitcnt vmcnt(5)
	v_mul_f32_e32 v22, 0xbfb8aa3b, v2
	v_mul_f32_e32 v23, 0xbfb8aa3b, v3
	s_waitcnt vmcnt(4)
	v_mul_f32_e32 v24, 0xbfb8aa3b, v28
	v_mul_f32_e32 v25, 0xbfb8aa3b, v29
	v_exp_f32_e32 v82, v22
	v_exp_f32_e32 v83, v23
	v_exp_f32_e32 v84, v24
	v_exp_f32_e32 v85, v25
	global_load_dwordx4 v[22:25], v[80:81], off
	global_load_dwordx4 v[232:235], v[80:81], off offset:16
	v_pk_add_f32 v[82:83], v[82:83], 1.0 op_sel_hi:[1,0]
	s_waitcnt lgkmcnt(1)
	v_pk_mul_f32 v[80:81], v[70:71], v[70:71]
	v_div_scale_f32 v130, s[0:1], v83, v83, v3
	v_pk_add_f32 v[84:85], v[84:85], 1.0 op_sel_hi:[1,0]
	v_div_scale_f32 v237, s[0:1], v82, v82, v2
	v_rcp_f32_e32 v242, v130
	v_div_scale_f32 v239, s[4:5], v85, v85, v29
	v_rcp_f32_e32 v243, v237
	v_rcp_f32_e32 v244, v239
	v_fma_f32 v246, -v130, v242, 1.0
	v_div_scale_f32 v236, vcc, v3, v83, v3
	v_fma_f32 v247, -v237, v243, 1.0
	v_fmac_f32_e32 v242, v246, v242
	v_div_scale_f32 v238, s[0:1], v2, v82, v2
	v_fma_f32 v248, -v239, v244, 1.0
	v_fmac_f32_e32 v243, v247, v243
	v_mul_f32_e32 v246, v236, v242
	v_div_scale_f32 v240, s[4:5], v29, v85, v29
	v_fmac_f32_e32 v244, v248, v244
	v_mul_f32_e32 v247, v238, v243
	v_fma_f32 v249, -v130, v246, v236
	v_div_scale_f32 v241, s[6:7], v84, v84, v28
	v_mul_f32_e32 v248, v240, v244
	v_fma_f32 v250, -v237, v247, v238
	v_fmac_f32_e32 v246, v249, v242
	v_rcp_f32_e32 v245, v241
	v_fma_f32 v251, -v239, v248, v240
	v_fmac_f32_e32 v247, v250, v243
	v_fma_f32 v130, -v130, v246, v236
	v_fmac_f32_e32 v248, v251, v244
	v_fma_f32 v236, -v237, v247, v238
	v_div_fmas_f32 v130, v130, v242, v246
	s_mov_b64 vcc, s[0:1]
	v_fma_f32 v237, -v239, v248, v240
	v_div_fixup_f32 v3, v130, v83, v3
	v_div_fmas_f32 v83, v236, v243, v247
	s_mov_b64 vcc, s[4:5]
	v_div_fixup_f32 v2, v83, v82, v2
	v_div_fmas_f32 v82, v237, v244, v248
	v_div_fixup_f32 v29, v82, v85, v29
	v_fma_f32 v82, -v241, v245, 1.0
	v_fmac_f32_e32 v245, v82, v245
	v_mul_f32_e32 v82, 0xbfb8aa3b, v26
	v_mul_f32_e32 v83, 0xbfb8aa3b, v27
	v_exp_f32_e32 v82, v82
	v_exp_f32_e32 v83, v83
	v_div_scale_f32 v85, vcc, v28, v84, v28
	v_mul_f32_e32 v130, v85, v245
	v_fma_f32 v236, -v241, v130, v85
	v_fmac_f32_e32 v130, v236, v245
	v_pk_add_f32 v[236:237], v[82:83], 1.0 op_sel_hi:[1,0]
	v_fma_f32 v85, -v241, v130, v85
	v_div_scale_f32 v82, s[0:1], v237, v237, v27
	v_rcp_f32_e32 v83, v82
	v_div_fmas_f32 v85, v85, v245, v130
	v_div_fixup_f32 v28, v85, v84, v28
	s_waitcnt lgkmcnt(0)
	v_pk_mul_f32 v[84:85], v[72:73], v[72:73]
	v_fma_f32 v130, -v82, v83, 1.0
	v_fmac_f32_e32 v83, v130, v83
	v_div_scale_f32 v130, vcc, v27, v237, v27
	v_mul_f32_e32 v238, v130, v83
	v_fma_f32 v239, -v82, v238, v130
	v_fmac_f32_e32 v238, v239, v83
	v_fma_f32 v82, -v82, v238, v130
	v_div_scale_f32 v130, s[0:1], v236, v236, v26
	v_rcp_f32_e32 v240, v130
	v_div_fmas_f32 v82, v82, v83, v238
	v_div_fixup_f32 v27, v82, v237, v27
	v_fma_f32 v82, -v130, v240, 1.0
	v_fmac_f32_e32 v240, v82, v240
	v_div_scale_f32 v82, vcc, v26, v236, v26
	v_mul_f32_e32 v83, v82, v240
	v_fma_f32 v237, -v130, v83, v82
	v_fmac_f32_e32 v83, v237, v240
	v_fma_f32 v82, -v130, v83, v82
	s_waitcnt vmcnt(0)
	v_mul_f32_e32 v130, 0xbfb8aa3b, v234
	v_exp_f32_e32 v238, v130
	v_mul_f32_e32 v130, 0xbfb8aa3b, v235
	v_exp_f32_e32 v239, v130
	v_div_fmas_f32 v130, v82, v240, v83
	v_div_fixup_f32 v26, v130, v236, v26
	ds_read2_b32 v[82:83], v230 offset0:6 offset1:7
	ds_read2_b32 v[236:237], v230 offset0:4 offset1:5
	v_pk_add_f32 v[238:239], v[238:239], 1.0 op_sel_hi:[1,0]
	s_waitcnt lgkmcnt(1)
	v_pk_mul_f32 v[240:241], v[82:83], v[82:83]
	v_div_scale_f32 v242, s[0:1], v239, v239, v235
	v_rcp_f32_e32 v243, v242
	s_nop 0
	v_fma_f32 v130, -v242, v243, 1.0
	v_fmac_f32_e32 v243, v130, v243
	v_div_scale_f32 v130, vcc, v235, v239, v235
	v_mul_f32_e32 v244, v130, v243
	v_fma_f32 v245, -v242, v244, v130
	v_fmac_f32_e32 v244, v245, v243
	v_div_scale_f32 v245, s[0:1], v238, v238, v234
	v_rcp_f32_e32 v246, v245
	v_fma_f32 v130, -v242, v244, v130
	v_div_fmas_f32 v130, v130, v243, v244
	v_div_fixup_f32 v235, v130, v239, v235
	v_fma_f32 v130, -v245, v246, 1.0
	v_fmac_f32_e32 v246, v130, v246
	v_div_scale_f32 v130, vcc, v234, v238, v234
	v_mul_f32_e32 v239, v130, v246
	v_fma_f32 v242, -v245, v239, v130
	v_fmac_f32_e32 v239, v242, v246
	v_mul_f32_e32 v242, 0xbfb8aa3b, v232
	v_mul_f32_e32 v243, 0xbfb8aa3b, v233
	v_exp_f32_e32 v242, v242
	v_exp_f32_e32 v243, v243
	v_fma_f32 v130, -v245, v239, v130
	v_div_fmas_f32 v130, v130, v246, v239
	v_div_fixup_f32 v234, v130, v238, v234
	v_pk_add_f32 v[242:243], v[242:243], 1.0 op_sel_hi:[1,0]
	ds_read2_b32 v[238:239], v230 offset0:2 offset1:3
	v_div_scale_f32 v246, s[0:1], v243, v243, v233
	v_rcp_f32_e32 v247, v246
	s_waitcnt lgkmcnt(1)
	v_pk_mul_f32 v[244:245], v[236:237], v[236:237]
	v_fma_f32 v130, -v246, v247, 1.0
	v_fmac_f32_e32 v247, v130, v247
	v_div_scale_f32 v130, vcc, v233, v243, v233
	v_mul_f32_e32 v248, v130, v247
	v_fma_f32 v249, -v246, v248, v130
	v_fmac_f32_e32 v248, v249, v247
	v_div_scale_f32 v249, s[0:1], v242, v242, v232
	v_rcp_f32_e32 v250, v249
	v_fma_f32 v130, -v246, v248, v130
	v_div_fmas_f32 v130, v130, v247, v248
	v_div_fixup_f32 v233, v130, v243, v233
	v_fma_f32 v130, -v249, v250, 1.0
	v_fmac_f32_e32 v250, v130, v250
	v_div_scale_f32 v130, vcc, v232, v242, v232
	v_mul_f32_e32 v243, v130, v250
	v_fma_f32 v246, -v249, v243, v130
	v_fmac_f32_e32 v243, v246, v250
	v_mul_f32_e32 v246, 0xbfb8aa3b, v24
	v_mul_f32_e32 v247, 0xbfb8aa3b, v25
	v_exp_f32_e32 v246, v246
	v_exp_f32_e32 v247, v247
	v_fma_f32 v130, -v249, v243, v130
	v_div_fmas_f32 v130, v130, v250, v243
	v_div_fixup_f32 v232, v130, v242, v232
	v_pk_add_f32 v[246:247], v[246:247], 1.0 op_sel_hi:[1,0]
	ds_read2_b32 v[242:243], v230 offset1:1
	v_div_scale_f32 v250, s[0:1], v247, v247, v25
	v_rcp_f32_e32 v251, v250
	s_waitcnt lgkmcnt(1)
	v_pk_mul_f32 v[248:249], v[238:239], v[238:239]
	v_fma_f32 v130, -v250, v251, 1.0
	v_fmac_f32_e32 v251, v130, v251
	v_div_scale_f32 v130, vcc, v25, v247, v25
	v_mul_f32_e32 v201, v130, v251
	v_fma_f32 v202, -v250, v201, v130
	v_fmac_f32_e32 v201, v202, v251
	v_div_scale_f32 v202, s[0:1], v246, v246, v24
	v_fma_f32 v130, -v250, v201, v130
	v_rcp_f32_e32 v92, v202
	v_div_fmas_f32 v130, v130, v251, v201
	v_div_fixup_f32 v25, v130, v247, v25
	v_mul_f32_e32 v247, 0xbfb8aa3b, v22
	v_exp_f32_e32 v250, v247
	v_mul_f32_e32 v247, 0xbfb8aa3b, v23
	v_fma_f32 v130, -v202, v92, 1.0
	v_exp_f32_e32 v251, v247
	v_fmac_f32_e32 v92, v130, v92
	v_div_scale_f32 v130, vcc, v24, v246, v24
	v_mul_f32_e32 v201, v130, v92
	v_fma_f32 v247, -v202, v201, v130
	v_fmac_f32_e32 v201, v247, v92
	v_pk_add_f32 v[250:251], v[250:251], 1.0 op_sel_hi:[1,0]
	v_fma_f32 v130, -v202, v201, v130
	v_div_scale_f32 v202, s[0:1], v251, v251, v23
	v_rcp_f32_e32 v91, v202
	v_div_fmas_f32 v92, v130, v92, v201
	v_div_fixup_f32 v24, v92, v246, v24
	s_waitcnt lgkmcnt(0)
	v_pk_mul_f32 v[246:247], v[242:243], v[242:243]
	v_fma_f32 v92, -v202, v91, 1.0
	v_fmac_f32_e32 v91, v92, v91
	v_div_scale_f32 v92, vcc, v23, v251, v23
	v_mul_f32_e32 v130, v92, v91
	v_fma_f32 v201, -v202, v130, v92
	v_fmac_f32_e32 v130, v201, v91
	v_fma_f32 v92, -v202, v130, v92
	v_div_fmas_f32 v91, v92, v91, v130
	v_add_f32_e32 v130, v246, v247
	v_add_f32_e32 v130, v130, v248
	v_add_f32_e32 v130, v130, v249
	v_add_f32_e32 v130, v130, v244
	v_add_f32_e32 v130, v130, v245
	v_add_f32_e32 v130, v130, v240
	v_add_f32_e32 v130, v130, v241
	v_add_f32_e32 v84, v130, v84
	v_add_f32_e32 v84, v84, v85
	v_add_f32_e32 v80, v84, v80
	v_add_f32_e32 v80, v80, v81
	v_add_f32_e32 v78, v80, v78
	v_add_f32_e32 v78, v78, v79
	v_add_f32_e32 v76, v78, v76
	v_add_f32_e32 v76, v76, v77
	ds_bpermute_b32 v69, v69, v76
	v_div_fixup_f32 v23, v91, v251, v23
	v_div_scale_f32 v91, s[0:1], v250, v250, v22
	v_rcp_f32_e32 v92, v91
	s_waitcnt lgkmcnt(0)
	v_add_f32_e32 v69, v76, v69
	ds_bpermute_b32 v76, v231, v69
	v_lshlrev_b32_e32 v130, 1, v54
	v_fma_f32 v77, -v91, v92, 1.0
	v_fmac_f32_e32 v92, v77, v92
	v_div_scale_f32 v77, vcc, v22, v250, v22
	s_waitcnt lgkmcnt(0)
	v_add_f32_e32 v69, v69, v76
	v_fmamk_f32 v69, v69, 0x3c800000, v197
	v_mul_f32_e32 v76, 0x4b800000, v69
	v_cmp_gt_f32_e64 s[0:1], s14, v69
	v_mul_f32_e32 v78, v77, v92
	v_fma_f32 v79, -v91, v78, v77
	v_cndmask_b32_e64 v69, v69, v76, s[0:1]
	v_rsq_f32_e32 v69, v69
	v_fmac_f32_e32 v78, v79, v92
	v_fma_f32 v77, -v91, v78, v77
	v_div_fmas_f32 v76, v77, v92, v78
	v_div_fixup_f32 v22, v76, v250, v22
	v_mul_f32_e32 v76, 0x45800000, v69
	v_cndmask_b32_e64 v76, v69, v76, s[0:1]
	v_pk_mul_f32 v[78:79], v[242:243], v[76:77] op_sel_hi:[1,0]
	s_nop 0
	v_pk_mul_f32 v[18:19], v[18:19], v[78:79]
	s_nop 0
	v_pk_mul_f32 v[18:19], v[22:23], v[18:19]
	v_pk_mul_f32 v[22:23], v[238:239], v[76:77] op_sel_hi:[1,0]
	v_cvt_pk_bf16_f32 v18, v18, v19
	v_pk_mul_f32 v[20:21], v[20:21], v[22:23]
	s_nop 0
	v_pk_mul_f32 v[20:21], v[24:25], v[20:21]
	s_nop 0
	v_cvt_pk_bf16_f32 v19, v20, v21
	v_pk_mul_f32 v[20:21], v[236:237], v[76:77] op_sel_hi:[1,0]
	s_nop 0
	v_pk_mul_f32 v[14:15], v[14:15], v[20:21]
	s_nop 0
	v_pk_mul_f32 v[14:15], v[14:15], v[232:233]
	s_nop 0
	v_cvt_pk_bf16_f32 v20, v14, v15
	v_pk_mul_f32 v[14:15], v[82:83], v[76:77] op_sel_hi:[1,0]
	s_nop 0
	v_pk_mul_f32 v[14:15], v[14:15], v[16:17]
	s_nop 0
	v_pk_mul_f32 v[14:15], v[14:15], v[234:235]
	s_nop 0
	v_cvt_pk_bf16_f32 v21, v14, v15
	v_pk_mul_f32 v[14:15], v[72:73], v[76:77] op_sel_hi:[1,0]
	s_nop 0
	v_pk_mul_f32 v[10:11], v[14:15], v[10:11]
	v_pk_mul_f32 v[14:15], v[70:71], v[76:77] op_sel_hi:[1,0]
	v_pk_mul_f32 v[10:11], v[10:11], v[26:27]
	v_pk_mul_f32 v[12:13], v[14:15], v[12:13]
	v_cvt_pk_bf16_f32 v10, v10, v11
	v_pk_mul_f32 v[12:13], v[12:13], v[28:29]
	v_pk_mul_f32 v[14:15], v[32:33], v[76:77] op_sel_hi:[1,0]
	v_cvt_pk_bf16_f32 v11, v12, v13
	v_mul_f32_e32 v12, 0xbfb8aa3b, v4
	v_mul_f32_e32 v13, 0xbfb8aa3b, v5
	v_exp_f32_e32 v12, v12
	v_exp_f32_e32 v13, v13
	v_pk_mul_f32 v[6:7], v[14:15], v[6:7]
	s_nop 0
	v_pk_mul_f32 v[2:3], v[6:7], v[2:3]
	v_pk_add_f32 v[6:7], v[12:13], 1.0 op_sel_hi:[1,0]
	v_cvt_pk_bf16_f32 v12, v2, v3
	v_div_scale_f32 v13, s[0:1], v7, v7, v5
	v_rcp_f32_e32 v14, v13
	v_pk_mul_f32 v[2:3], v[30:31], v[76:77] op_sel_hi:[1,0]
	s_nop 0
	v_pk_mul_f32 v[2:3], v[2:3], v[8:9]
	v_fma_f32 v8, -v13, v14, 1.0
	v_fmac_f32_e32 v14, v8, v14
	v_div_scale_f32 v8, vcc, v5, v7, v5
	v_mul_f32_e32 v9, v8, v14
	v_fma_f32 v15, -v13, v9, v8
	v_fmac_f32_e32 v9, v15, v14
	v_fma_f32 v8, -v13, v9, v8
	v_div_scale_f32 v13, s[0:1], v6, v6, v4
	v_rcp_f32_e32 v15, v13
	v_div_fmas_f32 v8, v8, v14, v9
	v_div_fixup_f32 v5, v8, v7, v5
	v_readlane_b32 s0, v252, 2
	v_fma_f32 v7, -v13, v15, 1.0
	v_fmac_f32_e32 v15, v7, v15
	v_div_scale_f32 v7, vcc, v4, v6, v4
	v_mul_f32_e32 v8, v7, v15
	v_fma_f32 v9, -v13, v8, v7
	v_fmac_f32_e32 v8, v9, v15
	v_fma_f32 v7, -v13, v8, v7
	v_div_fmas_f32 v7, v7, v15, v8
	v_div_fixup_f32 v4, v7, v6, v4
	v_pk_mul_f32 v[2:3], v[2:3], v[4:5]
	v_readlane_b32 s1, v252, 3
	v_cvt_pk_bf16_f32 v13, v2, v3
	v_lshl_add_u64 v[2:3], v[74:75], 0, v[130:131]
	global_store_dwordx4 v[2:3], v[18:21], off
	global_store_dwordx4 v[2:3], v[10:13], off offset:16
	s_load_dword s0, s[0:1], 0x0
	s_waitcnt lgkmcnt(0)
	v_readlane_b32 s16, v255, 45
	s_nop 0
	s_add_i32 s16, s0, s16
	s_cmpk_gt_i32 s16, 0x3ff
	s_cbranch_scc1 .LBB0_165
.LBB0_99:
	v_writelane_b32 v255, s16, 45
	s_and_b32 s0, s16, 0x3c0
	s_and_b32 s4, s16, 7
	s_lshl_b32 s4, s4, 3
	s_or_b32 s0, s0, s4
	s_bfe_u32 s4, s16, 0x30003
	s_or_b32 s16, s0, s4
	s_cmpk_gt_i32 s16, 0x1ff
	s_cselect_b64 s[54:55], -1, 0
	s_cmpk_lt_i32 s16, 0x200
	s_cselect_b64 s[4:5], -1, 0
	s_lshl_b32 s0, s16, 4
	s_and_b32 s27, s16, 3
	s_and_b32 s25, s0, 0x1fc0
	s_lshl_b32 s22, s27, 6
	s_and_b64 vcc, exec, s[54:55]
	s_waitcnt vmcnt(63) expcnt(7) lgkmcnt(15)
	s_barrier
	ds_write_b32 v209, v131
	ds_write_b32 v210, v131
	ds_write_b32 v211, v131
	ds_write_b32 v212, v131
	ds_write_b32 v213, v131
	ds_write_b32 v214, v131
	ds_write_b32 v215, v131
	ds_write_b32 v216, v131
	ds_write_b32 v217, v131
	ds_write_b32 v218, v131
	ds_write_b32 v219, v131
	ds_write_b32 v220, v131
	ds_write_b32 v221, v131
	ds_write_b32 v222, v131
	ds_write_b32 v223, v131
	ds_write_b32 v224, v131
	s_cbranch_vccnz .LBB0_101
	s_lshl_b32 s92, s22, 2
	v_ashrrev_i32_e32 v2, 4, v35
	v_lshl_add_u64 v[6:7], v[38:39], 0, s[92:93]
	v_add_u32_e32 v2, s25, v2
	v_mad_i64_i32 v[2:3], s[0:1], v2, s12, v[6:7]
	global_load_dwordx4 v[2:5], v[2:3], off
	v_add_u32_e32 v8, 0x8200, v225
	s_waitcnt vmcnt(0)
	ds_write2_b32 v8, v2, v3 offset1:1
	v_add_u32_e32 v2, 0x8208, v225
	ds_write2_b32 v2, v4, v5 offset1:1
	v_add_u32_e32 v2, s25, v93
	v_mad_i64_i32 v[2:3], s[0:1], v2, s12, v[6:7]
	global_load_dwordx4 v[2:5], v[2:3], off
	v_add_u32_e32 v8, 0x8200, v226
	s_waitcnt vmcnt(0)
	ds_write2_b32 v8, v2, v3 offset1:1
	v_add_u32_e32 v2, 0x8208, v226
	ds_write2_b32 v2, v4, v5 offset1:1
	v_add_u32_e32 v2, s25, v94
	v_mad_i64_i32 v[2:3], s[0:1], v2, s12, v[6:7]
	global_load_dwordx4 v[2:5], v[2:3], off
	v_add_u32_e32 v8, 0x8200, v227
	s_waitcnt vmcnt(0)
	ds_write2_b32 v8, v2, v3 offset1:1
	v_add_u32_e32 v2, 0x8208, v227
	ds_write2_b32 v2, v4, v5 offset1:1
	v_add_u32_e32 v2, s25, v95
	v_mad_i64_i32 v[2:3], s[0:1], v2, s12, v[6:7]
	global_load_dwordx4 v[2:5], v[2:3], off
	v_add_u32_e32 v6, 0x8200, v228
	s_waitcnt vmcnt(0)
	ds_write2_b32 v6, v2, v3 offset1:1
	v_add_u32_e32 v2, 0x8208, v228
	ds_write2_b32 v2, v4, v5 offset1:1

.LBB0_314:
	v_readlane_b32 s16, v255, 45
	v_readlane_b32 s10, v252, 2
	v_readlane_b32 s11, v252, 3
	s_load_dword s10, s[10:11], 0x0
	s_waitcnt lgkmcnt(0)
	s_add_i32 s16, s16, s10
	s_cmpk_gt_i32 s16, 0x7ff
	s_cbranch_scc1 .LBB0_400
.LBB0_315:
	v_writelane_b32 v255, s16, 45
	s_and_b32 s10, s16, 0x780
	s_and_b32 s13, s16, 7
	s_lshl_b32 s13, s13, 4
	s_or_b32 s10, s10, s13
	s_bfe_u32 s13, s16, 0x40003
	s_or_b32 s16, s10, s13
	s_lshl_b32 s10, s16, 3
	s_and_b32 s13, s16, 0x3ff
	s_and_b32 s25, s16, 1
	s_bfe_u32 s27, s16, 0x20001
	s_and_b32 s22, s10, 0x1fc0
	s_cmpk_gt_i32 s16, 0x3ff
	s_mov_b64 s[10:11], -1
	s_waitcnt vmcnt(63) expcnt(7) lgkmcnt(15)
	s_barrier
	s_cbranch_scc0 .LBB0_319
	s_cmp_eq_u32 s25, 0
	s_cselect_b64 s[10:11], -1, 0
	s_lshl_b32 s64, s25, 9
	v_readlane_b32 s66, v253, 30
	v_readlane_b32 s67, v253, 31
	s_add_u32 s64, s66, s64
	s_addc_u32 s65, s67, 0
	s_lshl_b32 s92, s27, 7
	v_cndmask_b32_e64 v4, v72, v54, s[10:11]
	s_add_u32 s64, s64, s92
	v_add_u32_e32 v4, s22, v4
	s_addc_u32 s65, s65, 0
	v_mov_b32_e32 v47, v131
	v_ashrrev_i32_e32 v5, 31, v4
	v_lshl_add_u64 v[2:3], s[64:65], 0, v[46:47]
	v_lshlrev_b64 v[6:7], 10, v[4:5]
	v_lshl_add_u64 v[6:7], v[2:3], 0, v[6:7]
	global_load_dword v210, v[6:7], off
	v_cndmask_b32_e64 v5, v74, v73, s[10:11]
	v_add_u32_e32 v6, s22, v5
	v_ashrrev_i32_e32 v7, 31, v6
	v_lshlrev_b64 v[8:9], 10, v[6:7]
	v_lshl_add_u64 v[8:9], v[2:3], 0, v[8:9]
	global_load_dword v211, v[8:9], off
	v_cndmask_b32_e64 v5, v76, v75, s[10:11]
	v_add_u32_e32 v8, s22, v5
	v_ashrrev_i32_e32 v9, 31, v8
	v_lshlrev_b64 v[12:13], 10, v[8:9]
	v_lshl_add_u64 v[12:13], v[2:3], 0, v[12:13]
	global_load_dword v212, v[12:13], off
	v_cndmask_b32_e64 v5, v78, v77, s[10:11]
	v_add_u32_e32 v50, s22, v5
	v_ashrrev_i32_e32 v51, 31, v50
	v_lshlrev_b64 v[14:15], 10, v[50:51]
	v_lshl_add_u64 v[14:15], v[2:3], 0, v[14:15]
	global_load_dword v213, v[14:15], off
	v_cndmask_b32_e64 v5, v80, v79, s[10:11]
	v_add_u32_e32 v52, s22, v5
	v_ashrrev_i32_e32 v53, 31, v52
	v_lshlrev_b64 v[14:15], 10, v[52:53]
	v_lshl_add_u64 v[14:15], v[2:3], 0, v[14:15]
	global_load_dword v214, v[14:15], off
	v_cndmask_b32_e64 v5, v82, v81, s[10:11]
	v_add_u32_e32 v194, s22, v5
	v_ashrrev_i32_e32 v195, 31, v194
	v_lshlrev_b64 v[16:17], 10, v[194:195]
	v_lshl_add_u64 v[16:17], v[2:3], 0, v[16:17]
	global_load_dword v215, v[16:17], off
	v_cndmask_b32_e64 v5, v84, v83, s[10:11]
	v_add_u32_e32 v206, s22, v5
	v_ashrrev_i32_e32 v207, 31, v206
	v_lshlrev_b64 v[16:17], 10, v[206:207]
	v_lshl_add_u64 v[16:17], v[2:3], 0, v[16:17]
	global_load_dword v216, v[16:17], off
	v_cndmask_b32_e64 v5, v86, v85, s[10:11]
	v_add_u32_e32 v208, s22, v5
	v_ashrrev_i32_e32 v209, 31, v208
	v_lshlrev_b64 v[192:193], 10, v[208:209]
	v_lshl_add_u64 v[2:3], v[2:3], 0, v[192:193]
	global_load_dword v217, v[2:3], off
	s_waitcnt vmcnt(7)
	v_add_f32_e32 v10, 0, v210
	s_waitcnt vmcnt(6)
	v_add_f32_e32 v11, v10, v211
	s_waitcnt vmcnt(5)
	v_add_f32_e32 v12, v11, v212
	s_waitcnt vmcnt(4)
	v_add_f32_e32 v13, v12, v213
	s_waitcnt vmcnt(3)
	v_add_f32_e32 v15, v13, v214
	s_waitcnt vmcnt(2)
	v_add_f32_e32 v14, v15, v215
	s_waitcnt vmcnt(1)
	v_add_f32_e32 v16, v14, v216
	s_waitcnt vmcnt(0)
	v_add_f32_e32 v17, v16, v217
	v_mov_b64_e32 v[2:3], s[8:9]
	v_mad_i64_i32 v[4:5], s[64:65], v4, s15, v[2:3]
	v_lshl_add_u64 v[4:5], v[4:5], 0, s[92:93]
	v_lshl_add_u64 v[4:5], v[4:5], 0, v[46:47]
	global_load_dword v193, v[4:5], off offset:3584
	v_mad_i64_i32 v[4:5], s[64:65], v6, s15, v[2:3]
	v_lshl_add_u64 v[4:5], v[4:5], 0, s[92:93]
	v_lshl_add_u64 v[4:5], v[4:5], 0, v[46:47]
	global_load_dword v191, v[4:5], off offset:3584
	v_mad_i64_i32 v[4:5], s[64:65], v8, s15, v[2:3]
	v_lshl_add_u64 v[4:5], v[4:5], 0, s[92:93]
	v_lshl_add_u64 v[4:5], v[4:5], 0, v[46:47]
	global_load_dword v192, v[4:5], off offset:3584
	v_mad_i64_i32 v[4:5], s[64:65], v50, s15, v[2:3]
	v_lshl_add_u64 v[4:5], v[4:5], 0, s[92:93]
	v_lshl_add_u64 v[4:5], v[4:5], 0, v[46:47]
	global_load_dword v53, v[4:5], off offset:3584
	v_mad_i64_i32 v[4:5], s[64:65], v52, s15, v[2:3]
	v_lshl_add_u64 v[4:5], v[4:5], 0, s[92:93]
	v_lshl_add_u64 v[4:5], v[4:5], 0, v[46:47]
	global_load_dword v51, v[4:5], off offset:3584
	v_mad_i64_i32 v[4:5], s[64:65], v194, s15, v[2:3]
	v_lshl_add_u64 v[4:5], v[4:5], 0, s[92:93]
	v_lshl_add_u64 v[4:5], v[4:5], 0, v[46:47]
	global_load_dword v52, v[4:5], off offset:3584
	v_mad_i64_i32 v[4:5], s[64:65], v206, s15, v[2:3]
	v_mad_i64_i32 v[2:3], s[64:65], v208, s15, v[2:3]
	v_lshl_add_u64 v[4:5], v[4:5], 0, s[92:93]
	v_lshl_add_u64 v[2:3], v[2:3], 0, s[92:93]
	v_lshl_add_u64 v[4:5], v[4:5], 0, v[46:47]
	v_lshl_add_u64 v[2:3], v[2:3], 0, v[46:47]
	global_load_dword v50, v[4:5], off offset:3584
	global_load_dword v47, v[2:3], off offset:3584
	v_add_u32_e32 v6, 0x2000, v56
	ds_write_b32 v55, v17 offset:8448
	s_waitcnt lgkmcnt(0)
	s_barrier
	ds_read2_b32 v[4:5], v6 offset0:64 offset1:96
	ds_read2_b32 v[2:3], v6 offset0:128 offset1:160
	ds_read2_b32 v[6:7], v6 offset0:192 offset1:224
	v_add_u32_e32 v8, 0x2400, v56
	ds_read2_b32 v[8:9], v8 offset1:32
	s_waitcnt lgkmcnt(3)
	v_add_f32_e32 v194, 0, v4
	v_add_f32_e32 v4, v194, v5
	s_waitcnt lgkmcnt(2)
	v_add_f32_e32 v4, v4, v2
	v_add_f32_e32 v4, v4, v3
	s_waitcnt lgkmcnt(1)
	v_add_f32_e32 v4, v4, v6
	v_add_f32_e32 v4, v4, v7
	s_waitcnt lgkmcnt(0)
	v_add_f32_e32 v4, v4, v8
	v_add_f32_e32 v4, v4, v9
	s_and_saveexec_b64 s[64:65], s[20:21]
	s_cbranch_execz .LBB0_318
	v_mul_f32_e32 v195, 0x3fb8aa3b, v4
	v_exp_f32_e32 v195, v195
	v_readlane_b32 s66, v253, 44
	v_lshl_or_b32 v206, s13, 5, v19
	v_mov_b32_e32 v207, v131
	v_readlane_b32 s67, v253, 45
	s_nop 1
	v_lshl_add_u64 v[206:207], v[206:207], 2, s[66:67]
	global_store_dword v[206:207], v195, off
